# c6 = c4 + K-loop heads aligned to 64 bytes
# speedup vs baseline: 1.0059x; 1.0059x over previous
.LBB0_343:
	s_ashr_i32 s11, s10, 31
	s_lshl_b64 s[12:13], s[10:11], 20
	s_add_u32 s12, s26, s12
	s_addc_u32 s13, s27, s13
	s_and_b64 s[14:15], s[2:3], exec
	s_cselect_b32 s11, s13, s21
	s_cselect_b32 s75, s12, s20
	s_ashr_i32 s9, s8, 31
	s_lshl_b64 s[14:15], s[8:9], 20
	s_add_u32 s14, s28, s14
	s_addc_u32 s15, s29, s15
	s_and_b64 s[22:23], s[2:3], exec
	s_cselect_b32 s9, s15, s19
	s_cselect_b32 s76, s14, s18
	s_add_u32 s77, s18, 0x100
	s_addc_u32 s78, s19, 0
	s_add_u32 s18, s20, 0x80080
	s_addc_u32 s19, s21, 0
	s_add_u32 s79, s20, 0x100
	v_mov_b32_e32 v2, 0
	s_addc_u32 s80, s21, 0
	s_mov_b32 s81, -2
	v_mov_b32_e32 v3, v2
	v_mov_b32_e32 v4, v2
	v_mov_b32_e32 v5, v2
	v_mov_b32_e32 v6, v2
	v_mov_b32_e32 v7, v2
	v_mov_b32_e32 v8, v2
	v_mov_b32_e32 v9, v2
	v_mov_b32_e32 v18, v2
	v_mov_b32_e32 v19, v2
	v_mov_b32_e32 v20, v2
	v_mov_b32_e32 v21, v2
	v_mov_b32_e32 v22, v2
	v_mov_b32_e32 v23, v2
	v_mov_b32_e32 v24, v2
	v_mov_b32_e32 v25, v2
	v_mov_b32_e32 v34, v2
	v_mov_b32_e32 v35, v2
	v_mov_b32_e32 v36, v2
	v_mov_b32_e32 v37, v2
	v_mov_b32_e32 v38, v2
	v_mov_b32_e32 v39, v2
	v_mov_b32_e32 v40, v2
	v_mov_b32_e32 v41, v2
	v_mov_b32_e32 v50, v2
	v_mov_b32_e32 v51, v2
	v_mov_b32_e32 v52, v2
	v_mov_b32_e32 v53, v2
	v_mov_b32_e32 v54, v2
	v_mov_b32_e32 v55, v2
	v_mov_b32_e32 v56, v2
	v_mov_b32_e32 v57, v2
	v_mov_b32_e32 v10, v2
	v_mov_b32_e32 v11, v2
	v_mov_b32_e32 v12, v2
	v_mov_b32_e32 v13, v2
	v_mov_b32_e32 v14, v2
	v_mov_b32_e32 v15, v2
	v_mov_b32_e32 v16, v2
	v_mov_b32_e32 v17, v2
	v_mov_b32_e32 v26, v2
	v_mov_b32_e32 v27, v2
	v_mov_b32_e32 v28, v2
	v_mov_b32_e32 v29, v2
	v_mov_b32_e32 v30, v2
	v_mov_b32_e32 v31, v2
	v_mov_b32_e32 v32, v2
	v_mov_b32_e32 v33, v2
	v_mov_b32_e32 v42, v2
	v_mov_b32_e32 v43, v2
	v_mov_b32_e32 v44, v2
	v_mov_b32_e32 v45, v2
	v_mov_b32_e32 v46, v2
	v_mov_b32_e32 v47, v2
	v_mov_b32_e32 v48, v2
	v_mov_b32_e32 v49, v2
	v_mov_b32_e32 v58, v2
	v_mov_b32_e32 v59, v2
	v_mov_b32_e32 v60, v2
	v_mov_b32_e32 v61, v2
	v_mov_b32_e32 v62, v2
	v_mov_b32_e32 v63, v2
	v_mov_b32_e32 v64, v2
	v_mov_b32_e32 v65, v2
	v_mov_b32_e32 v66, v2
	v_mov_b32_e32 v67, v2
	v_mov_b32_e32 v68, v2
	v_mov_b32_e32 v69, v2
	v_mov_b32_e32 v70, v2
	v_mov_b32_e32 v71, v2
	v_mov_b32_e32 v72, v2
	v_mov_b32_e32 v73, v2
	v_mov_b32_e32 v82, v2
	v_mov_b32_e32 v83, v2
	v_mov_b32_e32 v84, v2
	v_mov_b32_e32 v85, v2
	v_mov_b32_e32 v86, v2
	v_mov_b32_e32 v87, v2
	v_mov_b32_e32 v88, v2
	v_mov_b32_e32 v89, v2
	v_mov_b32_e32 v98, v2
	v_mov_b32_e32 v99, v2
	v_mov_b32_e32 v100, v2
	v_mov_b32_e32 v101, v2
	v_mov_b32_e32 v102, v2
	v_mov_b32_e32 v103, v2
	v_mov_b32_e32 v104, v2
	v_mov_b32_e32 v105, v2
	v_mov_b32_e32 v114, v2
	v_mov_b32_e32 v115, v2
	v_mov_b32_e32 v116, v2
	v_mov_b32_e32 v117, v2
	v_mov_b32_e32 v118, v2
	v_mov_b32_e32 v119, v2
	v_mov_b32_e32 v120, v2
	v_mov_b32_e32 v121, v2
	v_mov_b32_e32 v74, v2
	v_mov_b32_e32 v75, v2
	v_mov_b32_e32 v76, v2
	v_mov_b32_e32 v77, v2
	v_mov_b32_e32 v78, v2
	v_mov_b32_e32 v79, v2
	v_mov_b32_e32 v80, v2
	v_mov_b32_e32 v81, v2
	v_mov_b32_e32 v90, v2
	v_mov_b32_e32 v91, v2
	v_mov_b32_e32 v92, v2
	v_mov_b32_e32 v93, v2
	v_mov_b32_e32 v94, v2
	v_mov_b32_e32 v95, v2
	v_mov_b32_e32 v96, v2
	v_mov_b32_e32 v97, v2
	v_mov_b32_e32 v106, v2
	v_mov_b32_e32 v107, v2
	v_mov_b32_e32 v108, v2
	v_mov_b32_e32 v109, v2
	v_mov_b32_e32 v110, v2
	v_mov_b32_e32 v111, v2
	v_mov_b32_e32 v112, v2
	v_mov_b32_e32 v113, v2
	v_mov_b32_e32 v122, v2
	v_mov_b32_e32 v123, v2
	v_mov_b32_e32 v124, v2
	v_mov_b32_e32 v125, v2
	v_mov_b32_e32 v126, v2
	v_mov_b32_e32 v127, v2
	v_mov_b32_e32 v128, v2
	v_mov_b32_e32 v129, v2
	.p2align 6

.LBB0_472:
	s_ashr_i32 s13, s12, 31
	s_lshl_b64 s[14:15], s[12:13], 15
	s_add_u32 s14, s28, s14
	s_addc_u32 s15, s29, s15
	s_and_b64 s[16:17], s[2:3], exec
	s_cselect_b32 s13, s15, s23
	s_cselect_b32 s76, s14, s22
	s_ashr_i32 s11, s10, 31
	s_lshl_b64 s[16:17], s[10:11], 15
	s_add_u32 s16, s30, s16
	s_addc_u32 s17, s31, s17
	s_and_b64 s[24:25], s[2:3], exec
	s_cselect_b32 s11, s17, s21
	s_cselect_b32 s77, s16, s20
	s_add_u32 s78, s20, 0x80000
	s_addc_u32 s79, s21, 0
	s_add_u32 s20, s22, 0x204000
	s_addc_u32 s21, s23, 0
	s_add_u32 s80, s22, 0x400000
	v_mov_b32_e32 v2, 0
	s_addc_u32 s81, s23, 0
	s_mov_b32 s82, -2
	v_mov_b32_e32 v3, v2
	v_mov_b32_e32 v4, v2
	v_mov_b32_e32 v5, v2
	v_mov_b32_e32 v6, v2
	v_mov_b32_e32 v7, v2
	s_waitcnt vmcnt(25)
	v_mov_b32_e32 v8, v2
	s_waitcnt vmcnt(24)
	v_mov_b32_e32 v9, v2
	s_waitcnt vmcnt(23)
	v_mov_b32_e32 v10, v2
	s_waitcnt vmcnt(22)
	v_mov_b32_e32 v11, v2
	s_waitcnt vmcnt(21)
	v_mov_b32_e32 v12, v2
	s_waitcnt vmcnt(20)
	v_mov_b32_e32 v13, v2
	s_waitcnt vmcnt(15)
	v_mov_b32_e32 v18, v2
	s_waitcnt vmcnt(14)
	v_mov_b32_e32 v19, v2
	s_waitcnt vmcnt(13)
	v_mov_b32_e32 v20, v2
	s_waitcnt vmcnt(12)
	v_mov_b32_e32 v21, v2
	s_waitcnt vmcnt(7)
	v_mov_b32_e32 v26, v2
	s_waitcnt vmcnt(6)
	v_mov_b32_e32 v27, v2
	s_waitcnt vmcnt(5)
	v_mov_b32_e32 v28, v2
	s_waitcnt vmcnt(4)
	v_mov_b32_e32 v29, v2
	v_mov_b32_e32 v34, v2
	v_mov_b32_e32 v35, v2
	v_mov_b32_e32 v36, v2
	v_mov_b32_e32 v37, v2
	v_mov_b32_e32 v42, v2
	v_mov_b32_e32 v43, v2
	v_mov_b32_e32 v44, v2
	v_mov_b32_e32 v45, v2
	v_mov_b32_e32 v50, v2
	v_mov_b32_e32 v51, v2
	v_mov_b32_e32 v52, v2
	v_mov_b32_e32 v53, v2
	v_mov_b32_e32 v14, v2
	v_mov_b32_e32 v15, v2
	v_mov_b32_e32 v16, v2
	v_mov_b32_e32 v17, v2
	v_mov_b32_e32 v22, v2
	v_mov_b32_e32 v23, v2
	v_mov_b32_e32 v24, v2
	v_mov_b32_e32 v25, v2
	s_waitcnt vmcnt(3)
	v_mov_b32_e32 v30, v2
	s_waitcnt vmcnt(2)
	v_mov_b32_e32 v31, v2
	s_waitcnt vmcnt(1)
	v_mov_b32_e32 v32, v2
	s_waitcnt vmcnt(0)
	v_mov_b32_e32 v33, v2
	v_mov_b32_e32 v38, v2
	v_mov_b32_e32 v39, v2
	v_mov_b32_e32 v40, v2
	v_mov_b32_e32 v41, v2
	v_mov_b32_e32 v46, v2
	v_mov_b32_e32 v47, v2
	v_mov_b32_e32 v48, v2
	v_mov_b32_e32 v49, v2
	v_mov_b32_e32 v54, v2
	v_mov_b32_e32 v55, v2
	v_mov_b32_e32 v56, v2
	v_mov_b32_e32 v57, v2
	v_mov_b32_e32 v58, v2
	v_mov_b32_e32 v59, v2
	v_mov_b32_e32 v60, v2
	v_mov_b32_e32 v61, v2
	v_mov_b32_e32 v62, v2
	v_mov_b32_e32 v63, v2
	v_mov_b32_e32 v64, v2
	v_mov_b32_e32 v65, v2
	v_mov_b32_e32 v66, v2
	v_mov_b32_e32 v67, v2
	v_mov_b32_e32 v68, v2
	v_mov_b32_e32 v69, v2
	v_mov_b32_e32 v70, v2
	v_mov_b32_e32 v71, v2
	v_mov_b32_e32 v72, v2
	v_mov_b32_e32 v73, v2
	v_mov_b32_e32 v74, v2
	v_mov_b32_e32 v75, v2
	v_mov_b32_e32 v76, v2
	v_mov_b32_e32 v77, v2
	v_mov_b32_e32 v82, v2
	v_mov_b32_e32 v83, v2
	v_mov_b32_e32 v84, v2
	v_mov_b32_e32 v85, v2
	v_mov_b32_e32 v90, v2
	v_mov_b32_e32 v91, v2
	v_mov_b32_e32 v92, v2
	v_mov_b32_e32 v93, v2
	v_mov_b32_e32 v98, v2
	v_mov_b32_e32 v99, v2
	v_mov_b32_e32 v100, v2
	v_mov_b32_e32 v101, v2
	v_mov_b32_e32 v106, v2
	v_mov_b32_e32 v107, v2
	v_mov_b32_e32 v108, v2
	v_mov_b32_e32 v109, v2
	v_mov_b32_e32 v110, v2
	v_mov_b32_e32 v111, v2
	v_mov_b32_e32 v112, v2
	v_mov_b32_e32 v113, v2
	v_mov_b32_e32 v78, v2
	v_mov_b32_e32 v79, v2
	v_mov_b32_e32 v80, v2
	v_mov_b32_e32 v81, v2
	v_mov_b32_e32 v86, v2
	v_mov_b32_e32 v87, v2
	v_mov_b32_e32 v88, v2
	v_mov_b32_e32 v89, v2
	v_mov_b32_e32 v94, v2
	v_mov_b32_e32 v95, v2
	v_mov_b32_e32 v96, v2
	v_mov_b32_e32 v97, v2
	v_mov_b32_e32 v102, v2
	v_mov_b32_e32 v103, v2
	v_mov_b32_e32 v104, v2
	v_mov_b32_e32 v105, v2
	v_mov_b32_e32 v114, v2
	v_mov_b32_e32 v115, v2
	v_mov_b32_e32 v116, v2
	v_mov_b32_e32 v117, v2
	v_mov_b32_e32 v118, v2
	v_mov_b32_e32 v119, v2
	v_mov_b32_e32 v120, v2
	v_mov_b32_e32 v121, v2
	v_mov_b32_e32 v122, v2
	v_mov_b32_e32 v123, v2
	v_mov_b32_e32 v124, v2
	v_mov_b32_e32 v125, v2
	v_mov_b32_e32 v126, v2
	v_mov_b32_e32 v127, v2
	v_mov_b32_e32 v128, v2
	v_mov_b32_e32 v129, v2
	.p2align 6

.LBB0_653:
	s_ashr_i32 s23, s22, 31
	s_lshl_b64 s[24:25], s[22:23], 20
	s_add_u32 s24, s35, s24
	s_addc_u32 s25, s36, s25
	s_and_b64 s[26:27], s[2:3], exec
	s_cselect_b32 s7, s25, s11
	s_cselect_b32 s9, s24, s10
	s_ashr_i32 s21, s20, 31
	s_lshl_b64 s[26:27], s[20:21], 20
	s_add_u32 s26, s37, s26
	s_addc_u32 s27, s40, s27
	s_and_b64 s[28:29], s[2:3], exec
	s_cselect_b32 s21, s27, s5
	s_cselect_b32 s23, s26, s4
	s_add_u32 s30, s4, 0x100
	s_addc_u32 s31, s5, 0
	s_add_u32 s4, s10, 0x80080
	s_addc_u32 s5, s11, 0
	s_add_u32 s33, s10, 0x100
	v_mov_b32_e32 v2, 0
	s_addc_u32 s73, s11, 0
	s_mov_b32 s74, -2
	v_mov_b32_e32 v3, v2
	v_mov_b32_e32 v4, v2
	v_mov_b32_e32 v5, v2
	v_mov_b32_e32 v6, v2
	v_mov_b32_e32 v7, v2
	s_waitcnt vmcnt(25)
	v_mov_b32_e32 v8, v2
	s_waitcnt vmcnt(24)
	v_mov_b32_e32 v9, v2
	s_waitcnt vmcnt(15)
	v_mov_b32_e32 v18, v2
	s_waitcnt vmcnt(14)
	v_mov_b32_e32 v19, v2
	s_waitcnt vmcnt(13)
	v_mov_b32_e32 v20, v2
	s_waitcnt vmcnt(12)
	v_mov_b32_e32 v21, v2
	s_waitcnt vmcnt(11)
	v_mov_b32_e32 v22, v2
	s_waitcnt vmcnt(10)
	v_mov_b32_e32 v23, v2
	s_waitcnt vmcnt(9)
	v_mov_b32_e32 v24, v2
	s_waitcnt vmcnt(8)
	v_mov_b32_e32 v25, v2
	v_mov_b32_e32 v34, v2
	v_mov_b32_e32 v35, v2
	v_mov_b32_e32 v36, v2
	v_mov_b32_e32 v37, v2
	v_mov_b32_e32 v38, v2
	v_mov_b32_e32 v39, v2
	v_mov_b32_e32 v40, v2
	v_mov_b32_e32 v41, v2
	v_mov_b32_e32 v50, v2
	v_mov_b32_e32 v51, v2
	v_mov_b32_e32 v52, v2
	v_mov_b32_e32 v53, v2
	v_mov_b32_e32 v54, v2
	v_mov_b32_e32 v55, v2
	v_mov_b32_e32 v56, v2
	v_mov_b32_e32 v57, v2
	v_mov_b32_e32 v10, v2
	v_mov_b32_e32 v11, v2
	v_mov_b32_e32 v12, v2
	v_mov_b32_e32 v13, v2
	v_mov_b32_e32 v14, v2
	v_mov_b32_e32 v15, v2
	v_mov_b32_e32 v16, v2
	v_mov_b32_e32 v17, v2
	s_waitcnt vmcnt(7)
	v_mov_b32_e32 v26, v2
	s_waitcnt vmcnt(6)
	v_mov_b32_e32 v27, v2
	s_waitcnt vmcnt(5)
	v_mov_b32_e32 v28, v2
	s_waitcnt vmcnt(4)
	v_mov_b32_e32 v29, v2
	s_waitcnt vmcnt(3)
	v_mov_b32_e32 v30, v2
	s_waitcnt vmcnt(2)
	v_mov_b32_e32 v31, v2
	s_waitcnt vmcnt(1)
	v_mov_b32_e32 v32, v2
	s_waitcnt vmcnt(0)
	v_mov_b32_e32 v33, v2
	v_mov_b32_e32 v42, v2
	v_mov_b32_e32 v43, v2
	v_mov_b32_e32 v44, v2
	v_mov_b32_e32 v45, v2
	v_mov_b32_e32 v46, v2
	v_mov_b32_e32 v47, v2
	v_mov_b32_e32 v48, v2
	v_mov_b32_e32 v49, v2
	v_mov_b32_e32 v58, v2
	v_mov_b32_e32 v59, v2
	v_mov_b32_e32 v60, v2
	v_mov_b32_e32 v61, v2
	v_mov_b32_e32 v62, v2
	v_mov_b32_e32 v63, v2
	v_mov_b32_e32 v64, v2
	v_mov_b32_e32 v65, v2
	v_mov_b32_e32 v66, v2
	v_mov_b32_e32 v67, v2
	v_mov_b32_e32 v68, v2
	v_mov_b32_e32 v69, v2
	v_mov_b32_e32 v70, v2
	v_mov_b32_e32 v71, v2
	v_mov_b32_e32 v72, v2
	v_mov_b32_e32 v73, v2
	v_mov_b32_e32 v82, v2
	v_mov_b32_e32 v83, v2
	v_mov_b32_e32 v84, v2
	v_mov_b32_e32 v85, v2
	v_mov_b32_e32 v86, v2
	v_mov_b32_e32 v87, v2
	v_mov_b32_e32 v88, v2
	v_mov_b32_e32 v89, v2
	v_mov_b32_e32 v98, v2
	v_mov_b32_e32 v99, v2
	v_mov_b32_e32 v100, v2
	v_mov_b32_e32 v101, v2
	v_mov_b32_e32 v102, v2
	v_mov_b32_e32 v103, v2
	v_mov_b32_e32 v104, v2
	v_mov_b32_e32 v105, v2
	v_mov_b32_e32 v114, v2
	v_mov_b32_e32 v115, v2
	v_mov_b32_e32 v116, v2
	v_mov_b32_e32 v117, v2
	v_mov_b32_e32 v118, v2
	v_mov_b32_e32 v119, v2
	v_mov_b32_e32 v120, v2
	v_mov_b32_e32 v121, v2
	v_mov_b32_e32 v74, v2
	v_mov_b32_e32 v75, v2
	v_mov_b32_e32 v76, v2
	v_mov_b32_e32 v77, v2
	v_mov_b32_e32 v78, v2
	v_mov_b32_e32 v79, v2
	v_mov_b32_e32 v80, v2
	v_mov_b32_e32 v81, v2
	v_mov_b32_e32 v90, v2
	v_mov_b32_e32 v91, v2
	v_mov_b32_e32 v92, v2
	v_mov_b32_e32 v93, v2
	v_mov_b32_e32 v94, v2
	v_mov_b32_e32 v95, v2
	v_mov_b32_e32 v96, v2
	v_mov_b32_e32 v97, v2
	v_mov_b32_e32 v106, v2
	v_mov_b32_e32 v107, v2
	v_mov_b32_e32 v108, v2
	v_mov_b32_e32 v109, v2
	v_mov_b32_e32 v110, v2
	v_mov_b32_e32 v111, v2
	v_mov_b32_e32 v112, v2
	v_mov_b32_e32 v113, v2
	v_mov_b32_e32 v122, v2
	v_mov_b32_e32 v123, v2
	v_mov_b32_e32 v124, v2
	v_mov_b32_e32 v125, v2
	v_mov_b32_e32 v126, v2
	v_mov_b32_e32 v127, v2
	v_mov_b32_e32 v128, v2
	v_mov_b32_e32 v129, v2
	.p2align 6

.LBB0_1052:
	s_ashr_i32 s13, s12, 31
	s_lshl_b64 s[14:15], s[12:13], 20
	s_add_u32 s14, s28, s14
	s_addc_u32 s15, s29, s15
	s_and_b64 s[16:17], s[2:3], exec
	s_cselect_b32 s13, s15, s23
	s_cselect_b32 s67, s14, s22
	s_ashr_i32 s11, s10, 31
	s_lshl_b64 s[16:17], s[10:11], 20
	s_add_u32 s16, s30, s16
	s_addc_u32 s17, s31, s17
	s_and_b64 s[24:25], s[2:3], exec
	s_cselect_b32 s11, s17, s21
	s_cselect_b32 s73, s16, s20
	s_add_u32 s74, s20, 0x100
	s_addc_u32 s75, s21, 0
	s_add_u32 s20, s22, 0x80080
	s_addc_u32 s21, s23, 0
	s_add_u32 s76, s22, 0x100
	v_mov_b32_e32 v2, 0
	s_addc_u32 s77, s23, 0
	s_mov_b32 s78, -2
	v_mov_b32_e32 v3, v2
	v_mov_b32_e32 v4, v2
	v_mov_b32_e32 v5, v2
	v_mov_b32_e32 v6, v2
	v_mov_b32_e32 v7, v2
	s_waitcnt vmcnt(25)
	v_mov_b32_e32 v8, v2
	s_waitcnt vmcnt(24)
	v_mov_b32_e32 v9, v2
	s_waitcnt vmcnt(15)
	v_mov_b32_e32 v18, v2
	s_waitcnt vmcnt(14)
	v_mov_b32_e32 v19, v2
	s_waitcnt vmcnt(13)
	v_mov_b32_e32 v20, v2
	s_waitcnt vmcnt(12)
	v_mov_b32_e32 v21, v2
	s_waitcnt vmcnt(11)
	v_mov_b32_e32 v22, v2
	s_waitcnt vmcnt(10)
	v_mov_b32_e32 v23, v2
	s_waitcnt vmcnt(9)
	v_mov_b32_e32 v24, v2
	s_waitcnt vmcnt(8)
	v_mov_b32_e32 v25, v2
	v_mov_b32_e32 v34, v2
	v_mov_b32_e32 v35, v2
	v_mov_b32_e32 v36, v2
	v_mov_b32_e32 v37, v2
	v_mov_b32_e32 v38, v2
	v_mov_b32_e32 v39, v2
	v_mov_b32_e32 v40, v2
	v_mov_b32_e32 v41, v2
	v_mov_b32_e32 v50, v2
	v_mov_b32_e32 v51, v2
	v_mov_b32_e32 v52, v2
	v_mov_b32_e32 v53, v2
	v_mov_b32_e32 v54, v2
	v_mov_b32_e32 v55, v2
	v_mov_b32_e32 v56, v2
	v_mov_b32_e32 v57, v2
	v_mov_b32_e32 v10, v2
	v_mov_b32_e32 v11, v2
	v_mov_b32_e32 v12, v2
	v_mov_b32_e32 v13, v2
	v_mov_b32_e32 v14, v2
	v_mov_b32_e32 v15, v2
	v_mov_b32_e32 v16, v2
	v_mov_b32_e32 v17, v2
	s_waitcnt vmcnt(7)
	v_mov_b32_e32 v26, v2
	s_waitcnt vmcnt(6)
	v_mov_b32_e32 v27, v2
	s_waitcnt vmcnt(5)
	v_mov_b32_e32 v28, v2
	s_waitcnt vmcnt(4)
	v_mov_b32_e32 v29, v2
	s_waitcnt vmcnt(3)
	v_mov_b32_e32 v30, v2
	s_waitcnt vmcnt(2)
	v_mov_b32_e32 v31, v2
	s_waitcnt vmcnt(1)
	v_mov_b32_e32 v32, v2
	s_waitcnt vmcnt(0)
	v_mov_b32_e32 v33, v2
	v_mov_b32_e32 v42, v2
	v_mov_b32_e32 v43, v2
	v_mov_b32_e32 v44, v2
	v_mov_b32_e32 v45, v2
	v_mov_b32_e32 v46, v2
	v_mov_b32_e32 v47, v2
	v_mov_b32_e32 v48, v2
	v_mov_b32_e32 v49, v2
	v_mov_b32_e32 v58, v2
	v_mov_b32_e32 v59, v2
	v_mov_b32_e32 v60, v2
	v_mov_b32_e32 v61, v2
	v_mov_b32_e32 v62, v2
	v_mov_b32_e32 v63, v2
	v_mov_b32_e32 v64, v2
	v_mov_b32_e32 v65, v2
	v_mov_b32_e32 v66, v2
	v_mov_b32_e32 v67, v2
	v_mov_b32_e32 v68, v2
	v_mov_b32_e32 v69, v2
	v_mov_b32_e32 v70, v2
	v_mov_b32_e32 v71, v2
	v_mov_b32_e32 v72, v2
	v_mov_b32_e32 v73, v2
	v_mov_b32_e32 v74, v2
	v_mov_b32_e32 v75, v2
	v_mov_b32_e32 v76, v2
	v_mov_b32_e32 v77, v2
	v_mov_b32_e32 v82, v2
	v_mov_b32_e32 v83, v2
	v_mov_b32_e32 v84, v2
	v_mov_b32_e32 v85, v2
	v_mov_b32_e32 v98, v2
	v_mov_b32_e32 v99, v2
	v_mov_b32_e32 v100, v2
	v_mov_b32_e32 v101, v2
	v_mov_b32_e32 v102, v2
	v_mov_b32_e32 v103, v2
	v_mov_b32_e32 v104, v2
	v_mov_b32_e32 v105, v2
	v_mov_b32_e32 v106, v2
	v_mov_b32_e32 v107, v2
	v_mov_b32_e32 v108, v2
	v_mov_b32_e32 v109, v2
	v_mov_b32_e32 v110, v2
	v_mov_b32_e32 v111, v2
	v_mov_b32_e32 v112, v2
	v_mov_b32_e32 v113, v2
	v_mov_b32_e32 v78, v2
	v_mov_b32_e32 v79, v2
	v_mov_b32_e32 v80, v2
	v_mov_b32_e32 v81, v2
	v_mov_b32_e32 v86, v2
	v_mov_b32_e32 v87, v2
	v_mov_b32_e32 v88, v2
	v_mov_b32_e32 v89, v2
	v_mov_b32_e32 v90, v2
	v_mov_b32_e32 v91, v2
	v_mov_b32_e32 v92, v2
	v_mov_b32_e32 v93, v2
	v_mov_b32_e32 v94, v2
	v_mov_b32_e32 v95, v2
	v_mov_b32_e32 v96, v2
	v_mov_b32_e32 v97, v2
	v_mov_b32_e32 v114, v2
	v_mov_b32_e32 v115, v2
	v_mov_b32_e32 v116, v2
	v_mov_b32_e32 v117, v2
	v_mov_b32_e32 v118, v2
	v_mov_b32_e32 v119, v2
	v_mov_b32_e32 v120, v2
	v_mov_b32_e32 v121, v2
	v_mov_b32_e32 v122, v2
	v_mov_b32_e32 v123, v2
	v_mov_b32_e32 v124, v2
	v_mov_b32_e32 v125, v2
	v_mov_b32_e32 v126, v2
	v_mov_b32_e32 v127, v2
	v_mov_b32_e32 v128, v2
	v_mov_b32_e32 v129, v2
	.p2align 6

.LBB0_1223:
	s_ashr_i32 s11, s10, 31
	s_lshl_b64 s[12:13], s[10:11], 20
	s_add_u32 s12, s26, s12
	s_addc_u32 s13, s27, s13
	s_and_b64 s[14:15], s[2:3], exec
	s_cselect_b32 s11, s13, s21
	s_cselect_b32 s66, s12, s20
	s_ashr_i32 s9, s8, 31
	s_lshl_b64 s[14:15], s[8:9], 20
	s_add_u32 s14, s28, s14
	s_addc_u32 s15, s29, s15
	s_and_b64 s[22:23], s[2:3], exec
	s_cselect_b32 s9, s15, s19
	s_cselect_b32 s67, s14, s18
	s_add_u32 s73, s18, 0x100
	s_addc_u32 s74, s19, 0
	s_add_u32 s18, s20, 0x80080
	s_addc_u32 s19, s21, 0
	s_add_u32 s75, s20, 0x100
	v_mov_b32_e32 v2, 0
	s_addc_u32 s76, s21, 0
	s_mov_b32 s77, -2
	v_mov_b32_e32 v3, v2
	v_mov_b32_e32 v4, v2
	v_mov_b32_e32 v5, v2
	v_mov_b32_e32 v6, v2
	v_mov_b32_e32 v7, v2
	v_mov_b32_e32 v8, v2
	v_mov_b32_e32 v9, v2
	v_mov_b32_e32 v18, v2
	v_mov_b32_e32 v19, v2
	v_mov_b32_e32 v20, v2
	v_mov_b32_e32 v21, v2
	v_mov_b32_e32 v22, v2
	v_mov_b32_e32 v23, v2
	v_mov_b32_e32 v24, v2
	v_mov_b32_e32 v25, v2
	v_mov_b32_e32 v34, v2
	v_mov_b32_e32 v35, v2
	v_mov_b32_e32 v36, v2
	v_mov_b32_e32 v37, v2
	v_mov_b32_e32 v38, v2
	v_mov_b32_e32 v39, v2
	v_mov_b32_e32 v40, v2
	v_mov_b32_e32 v41, v2
	v_mov_b32_e32 v50, v2
	v_mov_b32_e32 v51, v2
	v_mov_b32_e32 v52, v2
	v_mov_b32_e32 v53, v2
	v_mov_b32_e32 v54, v2
	v_mov_b32_e32 v55, v2
	v_mov_b32_e32 v56, v2
	v_mov_b32_e32 v57, v2
	v_mov_b32_e32 v10, v2
	v_mov_b32_e32 v11, v2
	v_mov_b32_e32 v12, v2
	v_mov_b32_e32 v13, v2
	v_mov_b32_e32 v14, v2
	v_mov_b32_e32 v15, v2
	v_mov_b32_e32 v16, v2
	v_mov_b32_e32 v17, v2
	v_mov_b32_e32 v26, v2
	v_mov_b32_e32 v27, v2
	v_mov_b32_e32 v28, v2
	v_mov_b32_e32 v29, v2
	v_mov_b32_e32 v30, v2
	v_mov_b32_e32 v31, v2
	v_mov_b32_e32 v32, v2
	v_mov_b32_e32 v33, v2
	v_mov_b32_e32 v42, v2
	v_mov_b32_e32 v43, v2
	v_mov_b32_e32 v44, v2
	v_mov_b32_e32 v45, v2
	v_mov_b32_e32 v46, v2
	v_mov_b32_e32 v47, v2
	v_mov_b32_e32 v48, v2
	v_mov_b32_e32 v49, v2
	v_mov_b32_e32 v58, v2
	v_mov_b32_e32 v59, v2
	v_mov_b32_e32 v60, v2
	v_mov_b32_e32 v61, v2
	v_mov_b32_e32 v62, v2
	v_mov_b32_e32 v63, v2
	v_mov_b32_e32 v64, v2
	v_mov_b32_e32 v65, v2
	v_mov_b32_e32 v66, v2
	v_mov_b32_e32 v67, v2
	v_mov_b32_e32 v68, v2
	v_mov_b32_e32 v69, v2
	v_mov_b32_e32 v70, v2
	v_mov_b32_e32 v71, v2
	v_mov_b32_e32 v72, v2
	v_mov_b32_e32 v73, v2
	v_mov_b32_e32 v82, v2
	v_mov_b32_e32 v83, v2
	v_mov_b32_e32 v84, v2
	v_mov_b32_e32 v85, v2
	v_mov_b32_e32 v86, v2
	v_mov_b32_e32 v87, v2
	v_mov_b32_e32 v88, v2
	v_mov_b32_e32 v89, v2
	v_mov_b32_e32 v98, v2
	v_mov_b32_e32 v99, v2
	v_mov_b32_e32 v100, v2
	v_mov_b32_e32 v101, v2
	v_mov_b32_e32 v102, v2
	v_mov_b32_e32 v103, v2
	v_mov_b32_e32 v104, v2
	v_mov_b32_e32 v105, v2
	v_mov_b32_e32 v114, v2
	v_mov_b32_e32 v115, v2
	v_mov_b32_e32 v116, v2
	v_mov_b32_e32 v117, v2
	v_mov_b32_e32 v118, v2
	v_mov_b32_e32 v119, v2
	v_mov_b32_e32 v120, v2
	v_mov_b32_e32 v121, v2
	v_mov_b32_e32 v74, v2
	v_mov_b32_e32 v75, v2
	v_mov_b32_e32 v76, v2
	v_mov_b32_e32 v77, v2
	v_mov_b32_e32 v78, v2
	v_mov_b32_e32 v79, v2
	v_mov_b32_e32 v80, v2
	v_mov_b32_e32 v81, v2
	v_mov_b32_e32 v90, v2
	v_mov_b32_e32 v91, v2
	v_mov_b32_e32 v92, v2
	v_mov_b32_e32 v93, v2
	v_mov_b32_e32 v94, v2
	v_mov_b32_e32 v95, v2
	v_mov_b32_e32 v96, v2
	v_mov_b32_e32 v97, v2
	v_mov_b32_e32 v106, v2
	v_mov_b32_e32 v107, v2
	v_mov_b32_e32 v108, v2
	v_mov_b32_e32 v109, v2
	v_mov_b32_e32 v110, v2
	v_mov_b32_e32 v111, v2
	v_mov_b32_e32 v112, v2
	v_mov_b32_e32 v113, v2
	v_mov_b32_e32 v122, v2
	v_mov_b32_e32 v123, v2
	v_mov_b32_e32 v124, v2
	v_mov_b32_e32 v125, v2
	v_mov_b32_e32 v126, v2
	v_mov_b32_e32 v127, v2
	v_mov_b32_e32 v128, v2
	v_mov_b32_e32 v129, v2
	.p2align 6

.LBB0_1356:
	s_ashr_i32 s13, s12, 31
	s_lshl_b64 s[14:15], s[12:13], 15
	s_add_u32 s14, s28, s14
	s_addc_u32 s15, s29, s15
	s_and_b64 s[16:17], s[2:3], exec
	s_cselect_b32 s13, s15, s23
	s_cselect_b32 s67, s14, s22
	s_ashr_i32 s11, s10, 31
	s_lshl_b64 s[16:17], s[10:11], 15
	s_add_u32 s16, s30, s16
	s_addc_u32 s17, s31, s17
	s_and_b64 s[24:25], s[2:3], exec
	s_cselect_b32 s11, s17, s21
	s_cselect_b32 s73, s16, s20
	s_add_u32 s74, s20, 0x80000
	s_addc_u32 s75, s21, 0
	s_add_u32 s20, s22, 0x204000
	s_addc_u32 s21, s23, 0
	s_add_u32 s76, s22, 0x400000
	v_mov_b32_e32 v2, 0
	s_addc_u32 s77, s23, 0
	s_mov_b32 s78, -2
	v_mov_b32_e32 v3, v2
	v_mov_b32_e32 v4, v2
	v_mov_b32_e32 v5, v2
	v_mov_b32_e32 v6, v2
	v_mov_b32_e32 v7, v2
	s_waitcnt vmcnt(25)
	v_mov_b32_e32 v8, v2
	s_waitcnt vmcnt(24)
	v_mov_b32_e32 v9, v2
	s_waitcnt vmcnt(15)
	v_mov_b32_e32 v18, v2
	s_waitcnt vmcnt(14)
	v_mov_b32_e32 v19, v2
	s_waitcnt vmcnt(13)
	v_mov_b32_e32 v20, v2
	s_waitcnt vmcnt(12)
	v_mov_b32_e32 v21, v2
	s_waitcnt vmcnt(11)
	v_mov_b32_e32 v22, v2
	s_waitcnt vmcnt(10)
	v_mov_b32_e32 v23, v2
	s_waitcnt vmcnt(9)
	v_mov_b32_e32 v24, v2
	s_waitcnt vmcnt(8)
	v_mov_b32_e32 v25, v2
	v_mov_b32_e32 v34, v2
	v_mov_b32_e32 v35, v2
	v_mov_b32_e32 v36, v2
	v_mov_b32_e32 v37, v2
	v_mov_b32_e32 v38, v2
	v_mov_b32_e32 v39, v2
	v_mov_b32_e32 v40, v2
	v_mov_b32_e32 v41, v2
	v_mov_b32_e32 v50, v2
	v_mov_b32_e32 v51, v2
	v_mov_b32_e32 v52, v2
	v_mov_b32_e32 v53, v2
	v_mov_b32_e32 v54, v2
	v_mov_b32_e32 v55, v2
	v_mov_b32_e32 v56, v2
	v_mov_b32_e32 v57, v2
	v_mov_b32_e32 v10, v2
	v_mov_b32_e32 v11, v2
	v_mov_b32_e32 v12, v2
	v_mov_b32_e32 v13, v2
	v_mov_b32_e32 v14, v2
	v_mov_b32_e32 v15, v2
	v_mov_b32_e32 v16, v2
	v_mov_b32_e32 v17, v2
	s_waitcnt vmcnt(7)
	v_mov_b32_e32 v26, v2
	s_waitcnt vmcnt(6)
	v_mov_b32_e32 v27, v2
	s_waitcnt vmcnt(5)
	v_mov_b32_e32 v28, v2
	s_waitcnt vmcnt(4)
	v_mov_b32_e32 v29, v2
	s_waitcnt vmcnt(3)
	v_mov_b32_e32 v30, v2
	s_waitcnt vmcnt(2)
	v_mov_b32_e32 v31, v2
	s_waitcnt vmcnt(1)
	v_mov_b32_e32 v32, v2
	s_waitcnt vmcnt(0)
	v_mov_b32_e32 v33, v2
	v_mov_b32_e32 v42, v2
	v_mov_b32_e32 v43, v2
	v_mov_b32_e32 v44, v2
	v_mov_b32_e32 v45, v2
	v_mov_b32_e32 v46, v2
	v_mov_b32_e32 v47, v2
	v_mov_b32_e32 v48, v2
	v_mov_b32_e32 v49, v2
	v_mov_b32_e32 v58, v2
	v_mov_b32_e32 v59, v2
	v_mov_b32_e32 v60, v2
	v_mov_b32_e32 v61, v2
	v_mov_b32_e32 v62, v2
	v_mov_b32_e32 v63, v2
	v_mov_b32_e32 v64, v2
	v_mov_b32_e32 v65, v2
	v_mov_b32_e32 v66, v2
	v_mov_b32_e32 v67, v2
	v_mov_b32_e32 v68, v2
	v_mov_b32_e32 v69, v2
	v_mov_b32_e32 v70, v2
	v_mov_b32_e32 v71, v2
	v_mov_b32_e32 v72, v2
	v_mov_b32_e32 v73, v2
	v_mov_b32_e32 v74, v2
	v_mov_b32_e32 v75, v2
	v_mov_b32_e32 v76, v2
	v_mov_b32_e32 v77, v2
	v_mov_b32_e32 v82, v2
	v_mov_b32_e32 v83, v2
	v_mov_b32_e32 v84, v2
	v_mov_b32_e32 v85, v2
	v_mov_b32_e32 v98, v2
	v_mov_b32_e32 v99, v2
	v_mov_b32_e32 v100, v2
	v_mov_b32_e32 v101, v2
	v_mov_b32_e32 v102, v2
	v_mov_b32_e32 v103, v2
	v_mov_b32_e32 v104, v2
	v_mov_b32_e32 v105, v2
	v_mov_b32_e32 v106, v2
	v_mov_b32_e32 v107, v2
	v_mov_b32_e32 v108, v2
	v_mov_b32_e32 v109, v2
	v_mov_b32_e32 v114, v2
	v_mov_b32_e32 v115, v2
	v_mov_b32_e32 v116, v2
	v_mov_b32_e32 v117, v2
	v_mov_b32_e32 v78, v2
	v_mov_b32_e32 v79, v2
	v_mov_b32_e32 v80, v2
	v_mov_b32_e32 v81, v2
	v_mov_b32_e32 v86, v2
	v_mov_b32_e32 v87, v2
	v_mov_b32_e32 v88, v2
	v_mov_b32_e32 v89, v2
	v_mov_b32_e32 v90, v2
	v_mov_b32_e32 v91, v2
	v_mov_b32_e32 v92, v2
	v_mov_b32_e32 v93, v2
	v_mov_b32_e32 v94, v2
	v_mov_b32_e32 v95, v2
	v_mov_b32_e32 v96, v2
	v_mov_b32_e32 v97, v2
	v_mov_b32_e32 v110, v2
	v_mov_b32_e32 v111, v2
	v_mov_b32_e32 v112, v2
	v_mov_b32_e32 v113, v2
	v_mov_b32_e32 v118, v2
	v_mov_b32_e32 v119, v2
	v_mov_b32_e32 v120, v2
	v_mov_b32_e32 v121, v2
	v_mov_b32_e32 v122, v2
	v_mov_b32_e32 v123, v2
	v_mov_b32_e32 v124, v2
	v_mov_b32_e32 v125, v2
	v_mov_b32_e32 v126, v2
	v_mov_b32_e32 v127, v2
	v_mov_b32_e32 v128, v2
	v_mov_b32_e32 v129, v2
	.p2align 6

.LBB0_1537:
	s_ashr_i32 s23, s22, 31
	s_lshl_b64 s[24:25], s[22:23], 20
	s_add_u32 s24, s41, s24
	s_addc_u32 s25, s42, s25
	s_and_b64 s[26:27], s[4:5], exec
	s_cselect_b32 s7, s25, s35
	s_cselect_b32 s23, s24, s34
	s_ashr_i32 s21, s20, 31
	s_lshl_b64 s[26:27], s[20:21], 20
	s_add_u32 s26, s43, s26
	s_addc_u32 s27, s46, s27
	s_and_b64 s[36:37], s[4:5], exec
	s_cselect_b32 s21, s27, s31
	s_cselect_b32 s29, s26, s30
	s_add_u32 s79, s30, 0x100
	s_addc_u32 s80, s31, 0
	s_add_u32 s30, s34, 0x80080
	s_addc_u32 s31, s35, 0
	s_add_u32 s81, s34, 0x100
	v_mov_b32_e32 v2, 0
	s_addc_u32 s82, s35, 0
	s_mov_b32 s83, -2
	v_mov_b32_e32 v3, v2
	v_mov_b32_e32 v4, v2
	v_mov_b32_e32 v5, v2
	v_mov_b32_e32 v6, v2
	v_mov_b32_e32 v7, v2
	s_waitcnt vmcnt(25)
	v_mov_b32_e32 v8, v2
	s_waitcnt vmcnt(24)
	v_mov_b32_e32 v9, v2
	s_waitcnt vmcnt(4)
	v_mov_b32_e32 v18, v2
	s_waitcnt vmcnt(14)
	v_mov_b32_e32 v19, v2
	s_waitcnt vmcnt(13)
	v_mov_b32_e32 v20, v2
	s_waitcnt vmcnt(12)
	v_mov_b32_e32 v21, v2
	s_waitcnt vmcnt(2)
	v_mov_b32_e32 v22, v2
	s_waitcnt vmcnt(10)
	v_mov_b32_e32 v23, v2
	s_waitcnt vmcnt(9)
	v_mov_b32_e32 v24, v2
	s_waitcnt vmcnt(8)
	v_mov_b32_e32 v25, v2
	v_mov_b32_e32 v34, v2
	v_mov_b32_e32 v35, v2
	v_mov_b32_e32 v36, v2
	v_mov_b32_e32 v37, v2
	v_mov_b32_e32 v38, v2
	v_mov_b32_e32 v39, v2
	v_mov_b32_e32 v40, v2
	v_mov_b32_e32 v41, v2
	v_mov_b32_e32 v66, v2
	v_mov_b32_e32 v67, v2
	v_mov_b32_e32 v68, v2
	v_mov_b32_e32 v69, v2
	v_mov_b32_e32 v70, v2
	v_mov_b32_e32 v71, v2
	v_mov_b32_e32 v72, v2
	v_mov_b32_e32 v73, v2
	v_mov_b32_e32 v10, v2
	v_mov_b32_e32 v11, v2
	v_mov_b32_e32 v12, v2
	v_mov_b32_e32 v13, v2
	v_mov_b32_e32 v14, v2
	v_mov_b32_e32 v15, v2
	v_mov_b32_e32 v16, v2
	v_mov_b32_e32 v17, v2
	s_waitcnt vmcnt(7)
	v_mov_b32_e32 v26, v2
	s_waitcnt vmcnt(6)
	v_mov_b32_e32 v27, v2
	s_waitcnt vmcnt(5)
	v_mov_b32_e32 v28, v2
	s_waitcnt vmcnt(4)
	v_mov_b32_e32 v29, v2
	s_waitcnt vmcnt(3)
	v_mov_b32_e32 v30, v2
	s_waitcnt vmcnt(2)
	v_mov_b32_e32 v31, v2
	s_waitcnt vmcnt(1)
	v_mov_b32_e32 v32, v2
	s_waitcnt vmcnt(0)
	v_mov_b32_e32 v33, v2
	v_mov_b32_e32 v42, v2
	v_mov_b32_e32 v43, v2
	v_mov_b32_e32 v44, v2
	v_mov_b32_e32 v45, v2
	v_mov_b32_e32 v50, v2
	v_mov_b32_e32 v51, v2
	v_mov_b32_e32 v52, v2
	v_mov_b32_e32 v53, v2
	v_mov_b32_e32 v74, v2
	v_mov_b32_e32 v75, v2
	v_mov_b32_e32 v76, v2
	v_mov_b32_e32 v77, v2
	v_mov_b32_e32 v78, v2
	v_mov_b32_e32 v79, v2
	v_mov_b32_e32 v80, v2
	v_mov_b32_e32 v81, v2
	v_mov_b32_e32 v82, v2
	v_mov_b32_e32 v83, v2
	v_mov_b32_e32 v84, v2
	v_mov_b32_e32 v85, v2
	v_mov_b32_e32 v86, v2
	v_mov_b32_e32 v87, v2
	v_mov_b32_e32 v88, v2
	v_mov_b32_e32 v89, v2
	v_mov_b32_e32 v98, v2
	v_mov_b32_e32 v99, v2
	v_mov_b32_e32 v100, v2
	v_mov_b32_e32 v101, v2
	v_mov_b32_e32 v102, v2
	v_mov_b32_e32 v103, v2
	v_mov_b32_e32 v104, v2
	v_mov_b32_e32 v105, v2
	v_mov_b32_e32 v114, v2
	v_mov_b32_e32 v115, v2
	v_mov_b32_e32 v116, v2
	v_mov_b32_e32 v117, v2
	v_mov_b32_e32 v118, v2
	v_mov_b32_e32 v119, v2
	v_mov_b32_e32 v120, v2
	v_mov_b32_e32 v121, v2
	v_mov_b32_e32 v130, v2
	v_mov_b32_e32 v131, v2
	v_mov_b32_e32 v132, v2
	v_mov_b32_e32 v133, v2
	v_mov_b32_e32 v134, v2
	v_mov_b32_e32 v135, v2
	v_mov_b32_e32 v136, v2
	v_mov_b32_e32 v137, v2
	v_mov_b32_e32 v90, v2
	v_mov_b32_e32 v91, v2
	v_mov_b32_e32 v92, v2
	v_mov_b32_e32 v93, v2
	v_mov_b32_e32 v94, v2
	v_mov_b32_e32 v95, v2
	v_mov_b32_e32 v96, v2
	v_mov_b32_e32 v97, v2
	v_mov_b32_e32 v106, v2
	v_mov_b32_e32 v107, v2
	v_mov_b32_e32 v108, v2
	v_mov_b32_e32 v109, v2
	v_mov_b32_e32 v110, v2
	v_mov_b32_e32 v111, v2
	v_mov_b32_e32 v112, v2
	v_mov_b32_e32 v113, v2
	v_mov_b32_e32 v122, v2
	v_mov_b32_e32 v123, v2
	v_mov_b32_e32 v124, v2
	v_mov_b32_e32 v125, v2
	v_mov_b32_e32 v126, v2
	v_mov_b32_e32 v127, v2
	v_mov_b32_e32 v128, v2
	v_mov_b32_e32 v129, v2
	v_mov_b32_e32 v138, v2
	v_mov_b32_e32 v139, v2
	v_mov_b32_e32 v140, v2
	v_mov_b32_e32 v141, v2
	v_mov_b32_e32 v142, v2
	v_mov_b32_e32 v143, v2
	v_mov_b32_e32 v144, v2
	v_mov_b32_e32 v145, v2
	.p2align 6

.LBB0_1784:
	s_ashr_i32 s11, s10, 31
	s_lshl_b64 s[12:13], s[10:11], 20
	s_add_u32 s12, s26, s12
	s_addc_u32 s13, s27, s13
	s_and_b64 s[14:15], s[2:3], exec
	s_cselect_b32 s11, s13, s21
	s_cselect_b32 s64, s12, s20
	s_ashr_i32 s9, s8, 31
	s_lshl_b64 s[14:15], s[8:9], 20
	s_add_u32 s14, s28, s14
	s_addc_u32 s15, s29, s15
	s_and_b64 s[22:23], s[2:3], exec
	s_cselect_b32 s9, s15, s19
	s_cselect_b32 s65, s14, s18
	s_add_u32 s66, s18, 0x100
	s_addc_u32 s67, s19, 0
	s_add_u32 s18, s20, 0x80080
	s_addc_u32 s19, s21, 0
	s_add_u32 s70, s20, 0x100
	v_mov_b32_e32 v2, 0
	s_addc_u32 s71, s21, 0
	s_mov_b32 s73, -2
	v_mov_b32_e32 v3, v2
	v_mov_b32_e32 v4, v2
	v_mov_b32_e32 v5, v2
	v_mov_b32_e32 v6, v2
	v_mov_b32_e32 v7, v2
	v_mov_b32_e32 v8, v2
	v_mov_b32_e32 v9, v2
	v_mov_b32_e32 v18, v2
	v_mov_b32_e32 v19, v2
	v_mov_b32_e32 v20, v2
	v_mov_b32_e32 v21, v2
	v_mov_b32_e32 v22, v2
	v_mov_b32_e32 v23, v2
	v_mov_b32_e32 v24, v2
	v_mov_b32_e32 v25, v2
	v_mov_b32_e32 v34, v2
	v_mov_b32_e32 v35, v2
	v_mov_b32_e32 v36, v2
	v_mov_b32_e32 v37, v2
	v_mov_b32_e32 v38, v2
	v_mov_b32_e32 v39, v2
	v_mov_b32_e32 v40, v2
	v_mov_b32_e32 v41, v2
	v_mov_b32_e32 v50, v2
	v_mov_b32_e32 v51, v2
	v_mov_b32_e32 v52, v2
	v_mov_b32_e32 v53, v2
	v_mov_b32_e32 v54, v2
	v_mov_b32_e32 v55, v2
	v_mov_b32_e32 v56, v2
	v_mov_b32_e32 v57, v2
	v_mov_b32_e32 v10, v2
	v_mov_b32_e32 v11, v2
	v_mov_b32_e32 v12, v2
	v_mov_b32_e32 v13, v2
	v_mov_b32_e32 v14, v2
	v_mov_b32_e32 v15, v2
	v_mov_b32_e32 v16, v2
	v_mov_b32_e32 v17, v2
	v_mov_b32_e32 v26, v2
	v_mov_b32_e32 v27, v2
	v_mov_b32_e32 v28, v2
	v_mov_b32_e32 v29, v2
	v_mov_b32_e32 v30, v2
	v_mov_b32_e32 v31, v2
	v_mov_b32_e32 v32, v2
	v_mov_b32_e32 v33, v2
	v_mov_b32_e32 v42, v2
	v_mov_b32_e32 v43, v2
	v_mov_b32_e32 v44, v2
	v_mov_b32_e32 v45, v2
	v_mov_b32_e32 v46, v2
	v_mov_b32_e32 v47, v2
	v_mov_b32_e32 v48, v2
	v_mov_b32_e32 v49, v2
	v_mov_b32_e32 v58, v2
	v_mov_b32_e32 v59, v2
	v_mov_b32_e32 v60, v2
	v_mov_b32_e32 v61, v2
	v_mov_b32_e32 v62, v2
	v_mov_b32_e32 v63, v2
	v_mov_b32_e32 v64, v2
	v_mov_b32_e32 v65, v2
	v_mov_b32_e32 v66, v2
	v_mov_b32_e32 v67, v2
	v_mov_b32_e32 v68, v2
	v_mov_b32_e32 v69, v2
	v_mov_b32_e32 v70, v2
	v_mov_b32_e32 v71, v2
	v_mov_b32_e32 v72, v2
	v_mov_b32_e32 v73, v2
	v_mov_b32_e32 v82, v2
	v_mov_b32_e32 v83, v2
	v_mov_b32_e32 v84, v2
	v_mov_b32_e32 v85, v2
	v_mov_b32_e32 v86, v2
	v_mov_b32_e32 v87, v2
	v_mov_b32_e32 v88, v2
	v_mov_b32_e32 v89, v2
	v_mov_b32_e32 v98, v2
	v_mov_b32_e32 v99, v2
	v_mov_b32_e32 v100, v2
	v_mov_b32_e32 v101, v2
	v_mov_b32_e32 v102, v2
	v_mov_b32_e32 v103, v2
	v_mov_b32_e32 v104, v2
	v_mov_b32_e32 v105, v2
	v_mov_b32_e32 v114, v2
	v_mov_b32_e32 v115, v2
	v_mov_b32_e32 v116, v2
	v_mov_b32_e32 v117, v2
	v_mov_b32_e32 v118, v2
	v_mov_b32_e32 v119, v2
	v_mov_b32_e32 v120, v2
	v_mov_b32_e32 v121, v2
	v_mov_b32_e32 v74, v2
	v_mov_b32_e32 v75, v2
	v_mov_b32_e32 v76, v2
	v_mov_b32_e32 v77, v2
	v_mov_b32_e32 v78, v2
	v_mov_b32_e32 v79, v2
	v_mov_b32_e32 v80, v2
	v_mov_b32_e32 v81, v2
	v_mov_b32_e32 v90, v2
	v_mov_b32_e32 v91, v2
	v_mov_b32_e32 v92, v2
	v_mov_b32_e32 v93, v2
	v_mov_b32_e32 v94, v2
	v_mov_b32_e32 v95, v2
	v_mov_b32_e32 v96, v2
	v_mov_b32_e32 v97, v2
	v_mov_b32_e32 v106, v2
	v_mov_b32_e32 v107, v2
	v_mov_b32_e32 v108, v2
	v_mov_b32_e32 v109, v2
	v_mov_b32_e32 v110, v2
	v_mov_b32_e32 v111, v2
	v_mov_b32_e32 v112, v2
	v_mov_b32_e32 v113, v2
	v_mov_b32_e32 v122, v2
	v_mov_b32_e32 v123, v2
	v_mov_b32_e32 v124, v2
	v_mov_b32_e32 v125, v2
	v_mov_b32_e32 v126, v2
	v_mov_b32_e32 v127, v2
	v_mov_b32_e32 v128, v2
	v_mov_b32_e32 v129, v2
	.p2align 6

.LBB0_1951:
	s_ashr_i32 s13, s12, 31
	s_lshl_b64 s[14:15], s[12:13], 15
	s_add_u32 s14, s28, s14
	s_addc_u32 s15, s29, s15
	s_and_b64 s[16:17], s[2:3], exec
	s_cselect_b32 s13, s15, s23
	s_cselect_b32 s65, s14, s22
	s_ashr_i32 s11, s10, 31
	s_lshl_b64 s[16:17], s[10:11], 15
	s_add_u32 s16, s30, s16
	s_addc_u32 s17, s31, s17
	s_and_b64 s[24:25], s[2:3], exec
	s_cselect_b32 s11, s17, s21
	s_cselect_b32 s66, s16, s20
	s_add_u32 s67, s20, 0x80000
	s_addc_u32 s70, s21, 0
	s_add_u32 s20, s22, 0x204000
	s_addc_u32 s21, s23, 0
	s_add_u32 s71, s22, 0x400000
	v_mov_b32_e32 v2, 0
	s_addc_u32 s73, s23, 0
	s_mov_b32 s74, -2
	v_mov_b32_e32 v3, v2
	v_mov_b32_e32 v4, v2
	v_mov_b32_e32 v5, v2
	v_mov_b32_e32 v6, v2
	v_mov_b32_e32 v7, v2
	s_waitcnt vmcnt(25)
	v_mov_b32_e32 v8, v2
	s_waitcnt vmcnt(24)
	v_mov_b32_e32 v9, v2
	s_waitcnt vmcnt(4)
	v_mov_b32_e32 v18, v2
	v_mov_b32_e32 v19, v2
	v_mov_b32_e32 v20, v2
	v_mov_b32_e32 v21, v2
	s_waitcnt vmcnt(2)
	v_mov_b32_e32 v22, v2
	v_mov_b32_e32 v23, v2
	v_mov_b32_e32 v24, v2
	v_mov_b32_e32 v25, v2
	v_mov_b32_e32 v34, v2
	v_mov_b32_e32 v35, v2
	v_mov_b32_e32 v36, v2
	v_mov_b32_e32 v37, v2
	v_mov_b32_e32 v38, v2
	v_mov_b32_e32 v39, v2
	v_mov_b32_e32 v40, v2
	v_mov_b32_e32 v41, v2
	v_mov_b32_e32 v50, v2
	v_mov_b32_e32 v51, v2
	v_mov_b32_e32 v52, v2
	v_mov_b32_e32 v53, v2
	v_mov_b32_e32 v54, v2
	v_mov_b32_e32 v55, v2
	v_mov_b32_e32 v56, v2
	v_mov_b32_e32 v57, v2
	v_mov_b32_e32 v10, v2
	v_mov_b32_e32 v11, v2
	v_mov_b32_e32 v12, v2
	v_mov_b32_e32 v13, v2
	v_mov_b32_e32 v14, v2
	v_mov_b32_e32 v15, v2
	v_mov_b32_e32 v16, v2
	v_mov_b32_e32 v17, v2
	v_mov_b32_e32 v26, v2
	v_mov_b32_e32 v27, v2
	v_mov_b32_e32 v28, v2
	v_mov_b32_e32 v29, v2
	v_mov_b32_e32 v30, v2
	v_mov_b32_e32 v31, v2
	s_waitcnt vmcnt(1)
	v_mov_b32_e32 v32, v2
	s_waitcnt vmcnt(0)
	v_mov_b32_e32 v33, v2
	v_mov_b32_e32 v42, v2
	v_mov_b32_e32 v43, v2
	v_mov_b32_e32 v44, v2
	v_mov_b32_e32 v45, v2
	v_mov_b32_e32 v46, v2
	v_mov_b32_e32 v47, v2
	v_mov_b32_e32 v48, v2
	v_mov_b32_e32 v49, v2
	v_mov_b32_e32 v58, v2
	v_mov_b32_e32 v59, v2
	v_mov_b32_e32 v60, v2
	v_mov_b32_e32 v61, v2
	v_mov_b32_e32 v62, v2
	v_mov_b32_e32 v63, v2
	v_mov_b32_e32 v64, v2
	v_mov_b32_e32 v65, v2
	v_mov_b32_e32 v66, v2
	v_mov_b32_e32 v67, v2
	v_mov_b32_e32 v68, v2
	v_mov_b32_e32 v69, v2
	v_mov_b32_e32 v70, v2
	v_mov_b32_e32 v71, v2
	v_mov_b32_e32 v72, v2
	v_mov_b32_e32 v73, v2
	v_mov_b32_e32 v74, v2
	v_mov_b32_e32 v75, v2
	v_mov_b32_e32 v76, v2
	v_mov_b32_e32 v77, v2
	v_mov_b32_e32 v82, v2
	v_mov_b32_e32 v83, v2
	v_mov_b32_e32 v84, v2
	v_mov_b32_e32 v85, v2
	v_mov_b32_e32 v98, v2
	v_mov_b32_e32 v99, v2
	v_mov_b32_e32 v100, v2
	v_mov_b32_e32 v101, v2
	v_mov_b32_e32 v102, v2
	v_mov_b32_e32 v103, v2
	v_mov_b32_e32 v104, v2
	v_mov_b32_e32 v105, v2
	v_mov_b32_e32 v106, v2
	v_mov_b32_e32 v107, v2
	v_mov_b32_e32 v108, v2
	v_mov_b32_e32 v109, v2
	v_mov_b32_e32 v114, v2
	v_mov_b32_e32 v115, v2
	v_mov_b32_e32 v116, v2
	v_mov_b32_e32 v117, v2
	v_mov_b32_e32 v78, v2
	v_mov_b32_e32 v79, v2
	v_mov_b32_e32 v80, v2
	v_mov_b32_e32 v81, v2
	v_mov_b32_e32 v86, v2
	v_mov_b32_e32 v87, v2
	v_mov_b32_e32 v88, v2
	v_mov_b32_e32 v89, v2
	v_mov_b32_e32 v90, v2
	v_mov_b32_e32 v91, v2
	v_mov_b32_e32 v92, v2
	v_mov_b32_e32 v93, v2
	v_mov_b32_e32 v94, v2
	v_mov_b32_e32 v95, v2
	v_mov_b32_e32 v96, v2
	v_mov_b32_e32 v97, v2
	v_mov_b32_e32 v110, v2
	v_mov_b32_e32 v111, v2
	v_mov_b32_e32 v112, v2
	v_mov_b32_e32 v113, v2
	v_mov_b32_e32 v118, v2
	v_mov_b32_e32 v119, v2
	v_mov_b32_e32 v120, v2
	v_mov_b32_e32 v121, v2
	v_mov_b32_e32 v122, v2
	v_mov_b32_e32 v123, v2
	v_mov_b32_e32 v124, v2
	v_mov_b32_e32 v125, v2
	v_mov_b32_e32 v126, v2
	v_mov_b32_e32 v127, v2
	v_mov_b32_e32 v128, v2
	v_mov_b32_e32 v129, v2
	.p2align 6

.LBB0_2145:
	s_ashr_i32 s25, s24, 31
	s_lshl_b64 s[26:27], s[24:25], 20
	s_add_u32 s26, s33, s26
	s_addc_u32 s27, s42, s27
	s_and_b64 s[28:29], s[2:3], exec
	s_cselect_b32 s5, s27, s37
	s_cselect_b32 s25, s26, s36
	s_ashr_i32 s23, s22, 31
	s_lshl_b64 s[28:29], s[22:23], 20
	s_add_u32 s28, s43, s28
	s_addc_u32 s29, s46, s29
	s_and_b64 s[40:41], s[2:3], exec
	s_cselect_b32 s23, s29, s35
	s_cselect_b32 s31, s28, s34
	s_add_u32 s77, s34, 0x100
	s_addc_u32 s78, s35, 0
	s_add_u32 s34, s36, 0x80080
	s_addc_u32 s35, s37, 0
	s_add_u32 s79, s36, 0x100
	v_mov_b32_e32 v2, 0
	s_addc_u32 s80, s37, 0
	s_mov_b32 s81, -2
	v_mov_b32_e32 v3, v2
	v_mov_b32_e32 v4, v2
	v_mov_b32_e32 v5, v2
	v_mov_b32_e32 v6, v2
	v_mov_b32_e32 v7, v2
	s_waitcnt vmcnt(25)
	v_mov_b32_e32 v8, v2
	s_waitcnt vmcnt(24)
	v_mov_b32_e32 v9, v2
	s_waitcnt vmcnt(4)
	v_mov_b32_e32 v18, v2
	v_mov_b32_e32 v19, v2
	v_mov_b32_e32 v20, v2
	v_mov_b32_e32 v21, v2
	s_waitcnt vmcnt(2)
	v_mov_b32_e32 v22, v2
	v_mov_b32_e32 v23, v2
	v_mov_b32_e32 v24, v2
	v_mov_b32_e32 v25, v2
	v_mov_b32_e32 v34, v2
	v_mov_b32_e32 v35, v2
	v_mov_b32_e32 v36, v2
	v_mov_b32_e32 v37, v2
	v_mov_b32_e32 v38, v2
	v_mov_b32_e32 v39, v2
	v_mov_b32_e32 v40, v2
	v_mov_b32_e32 v41, v2
	v_mov_b32_e32 v66, v2
	v_mov_b32_e32 v67, v2
	v_mov_b32_e32 v68, v2
	v_mov_b32_e32 v69, v2
	v_mov_b32_e32 v70, v2
	v_mov_b32_e32 v71, v2
	v_mov_b32_e32 v72, v2
	v_mov_b32_e32 v73, v2
	v_mov_b32_e32 v10, v2
	v_mov_b32_e32 v11, v2
	v_mov_b32_e32 v12, v2
	v_mov_b32_e32 v13, v2
	v_mov_b32_e32 v14, v2
	v_mov_b32_e32 v15, v2
	v_mov_b32_e32 v16, v2
	v_mov_b32_e32 v17, v2
	v_mov_b32_e32 v26, v2
	v_mov_b32_e32 v27, v2
	v_mov_b32_e32 v28, v2
	v_mov_b32_e32 v29, v2
	v_mov_b32_e32 v30, v2
	v_mov_b32_e32 v31, v2
	s_waitcnt vmcnt(1)
	v_mov_b32_e32 v32, v2
	s_waitcnt vmcnt(0)
	v_mov_b32_e32 v33, v2
	v_mov_b32_e32 v50, v2
	v_mov_b32_e32 v51, v2
	v_mov_b32_e32 v52, v2
	v_mov_b32_e32 v53, v2
	v_mov_b32_e32 v54, v2
	v_mov_b32_e32 v55, v2
	v_mov_b32_e32 v56, v2
	v_mov_b32_e32 v57, v2
	v_mov_b32_e32 v74, v2
	v_mov_b32_e32 v75, v2
	v_mov_b32_e32 v76, v2
	v_mov_b32_e32 v77, v2
	v_mov_b32_e32 v78, v2
	v_mov_b32_e32 v79, v2
	v_mov_b32_e32 v80, v2
	v_mov_b32_e32 v81, v2
	v_mov_b32_e32 v82, v2
	v_mov_b32_e32 v83, v2
	v_mov_b32_e32 v84, v2
	v_mov_b32_e32 v85, v2
	v_mov_b32_e32 v86, v2
	v_mov_b32_e32 v87, v2
	v_mov_b32_e32 v88, v2
	v_mov_b32_e32 v89, v2
	v_mov_b32_e32 v98, v2
	v_mov_b32_e32 v99, v2
	v_mov_b32_e32 v100, v2
	v_mov_b32_e32 v101, v2
	v_mov_b32_e32 v102, v2
	v_mov_b32_e32 v103, v2
	v_mov_b32_e32 v104, v2
	v_mov_b32_e32 v105, v2
	v_mov_b32_e32 v114, v2
	v_mov_b32_e32 v115, v2
	v_mov_b32_e32 v116, v2
	v_mov_b32_e32 v117, v2
	v_mov_b32_e32 v118, v2
	v_mov_b32_e32 v119, v2
	v_mov_b32_e32 v120, v2
	v_mov_b32_e32 v121, v2
	v_mov_b32_e32 v130, v2
	v_mov_b32_e32 v131, v2
	v_mov_b32_e32 v132, v2
	v_mov_b32_e32 v133, v2
	v_mov_b32_e32 v134, v2
	v_mov_b32_e32 v135, v2
	v_mov_b32_e32 v136, v2
	v_mov_b32_e32 v137, v2
	v_mov_b32_e32 v90, v2
	v_mov_b32_e32 v91, v2
	v_mov_b32_e32 v92, v2
	v_mov_b32_e32 v93, v2
	v_mov_b32_e32 v94, v2
	v_mov_b32_e32 v95, v2
	v_mov_b32_e32 v96, v2
	v_mov_b32_e32 v97, v2
	v_mov_b32_e32 v106, v2
	v_mov_b32_e32 v107, v2
	v_mov_b32_e32 v108, v2
	v_mov_b32_e32 v109, v2
	v_mov_b32_e32 v110, v2
	v_mov_b32_e32 v111, v2
	v_mov_b32_e32 v112, v2
	v_mov_b32_e32 v113, v2
	v_mov_b32_e32 v122, v2
	v_mov_b32_e32 v123, v2
	v_mov_b32_e32 v124, v2
	v_mov_b32_e32 v125, v2
	v_mov_b32_e32 v126, v2
	v_mov_b32_e32 v127, v2
	v_mov_b32_e32 v128, v2
	v_mov_b32_e32 v129, v2
	v_mov_b32_e32 v138, v2
	v_mov_b32_e32 v139, v2
	v_mov_b32_e32 v140, v2
	v_mov_b32_e32 v141, v2
	v_mov_b32_e32 v142, v2
	v_mov_b32_e32 v143, v2
	v_mov_b32_e32 v144, v2
	v_mov_b32_e32 v145, v2
	.p2align 6

.LBB0_2409:
	s_ashr_i32 s17, s16, 31
	s_lshl_b64 s[18:19], s[16:17], 20
	s_add_u32 s18, s33, s18
	s_addc_u32 s19, s34, s19
	s_and_b64 s[20:21], s[2:3], exec
	s_cselect_b32 s17, s19, s27
	s_cselect_b32 s71, s18, s26
	s_ashr_i32 s15, s14, 31
	s_lshl_b64 s[20:21], s[14:15], 20
	s_add_u32 s20, s35, s20
	s_addc_u32 s21, s36, s21
	s_and_b64 s[28:29], s[2:3], exec
	s_cselect_b32 s15, s21, s25
	s_cselect_b32 s73, s20, s24
	s_add_u32 s74, s24, 0x100
	s_addc_u32 s75, s25, 0
	s_add_u32 s24, s26, 0x80080
	s_addc_u32 s25, s27, 0
	s_add_u32 s76, s26, 0x100
	v_mov_b32_e32 v2, 0
	s_addc_u32 s77, s27, 0
	s_mov_b32 s78, -2
	v_mov_b32_e32 v3, v2
	v_mov_b32_e32 v4, v2
	v_mov_b32_e32 v5, v2
	v_mov_b32_e32 v6, v2
	v_mov_b32_e32 v7, v2
	s_waitcnt vmcnt(25)
	v_mov_b32_e32 v8, v2
	s_waitcnt vmcnt(24)
	v_mov_b32_e32 v9, v2
	s_waitcnt vmcnt(4)
	v_mov_b32_e32 v18, v2
	v_mov_b32_e32 v19, v2
	v_mov_b32_e32 v20, v2
	v_mov_b32_e32 v21, v2
	s_waitcnt vmcnt(2)
	v_mov_b32_e32 v22, v2
	v_mov_b32_e32 v23, v2
	v_mov_b32_e32 v24, v2
	v_mov_b32_e32 v25, v2
	v_mov_b32_e32 v34, v2
	v_mov_b32_e32 v35, v2
	v_mov_b32_e32 v36, v2
	v_mov_b32_e32 v37, v2
	v_mov_b32_e32 v38, v2
	v_mov_b32_e32 v39, v2
	v_mov_b32_e32 v40, v2
	v_mov_b32_e32 v41, v2
	v_mov_b32_e32 v50, v2
	v_mov_b32_e32 v51, v2
	v_mov_b32_e32 v52, v2
	v_mov_b32_e32 v53, v2
	v_mov_b32_e32 v54, v2
	v_mov_b32_e32 v55, v2
	v_mov_b32_e32 v56, v2
	v_mov_b32_e32 v57, v2
	v_mov_b32_e32 v10, v2
	v_mov_b32_e32 v11, v2
	v_mov_b32_e32 v12, v2
	v_mov_b32_e32 v13, v2
	v_mov_b32_e32 v14, v2
	v_mov_b32_e32 v15, v2
	v_mov_b32_e32 v16, v2
	v_mov_b32_e32 v17, v2
	v_mov_b32_e32 v26, v2
	v_mov_b32_e32 v27, v2
	v_mov_b32_e32 v28, v2
	v_mov_b32_e32 v29, v2
	v_mov_b32_e32 v30, v2
	v_mov_b32_e32 v31, v2
	s_waitcnt vmcnt(1)
	v_mov_b32_e32 v32, v2
	s_waitcnt vmcnt(0)
	v_mov_b32_e32 v33, v2
	v_mov_b32_e32 v42, v2
	v_mov_b32_e32 v43, v2
	v_mov_b32_e32 v44, v2
	v_mov_b32_e32 v45, v2
	v_mov_b32_e32 v46, v2
	v_mov_b32_e32 v47, v2
	v_mov_b32_e32 v48, v2
	v_mov_b32_e32 v49, v2
	v_mov_b32_e32 v58, v2
	v_mov_b32_e32 v59, v2
	v_mov_b32_e32 v60, v2
	v_mov_b32_e32 v61, v2
	v_mov_b32_e32 v62, v2
	v_mov_b32_e32 v63, v2
	v_mov_b32_e32 v64, v2
	v_mov_b32_e32 v65, v2
	v_mov_b32_e32 v66, v2
	v_mov_b32_e32 v67, v2
	v_mov_b32_e32 v68, v2
	v_mov_b32_e32 v69, v2
	v_mov_b32_e32 v70, v2
	v_mov_b32_e32 v71, v2
	v_mov_b32_e32 v72, v2
	v_mov_b32_e32 v73, v2
	v_mov_b32_e32 v74, v2
	v_mov_b32_e32 v75, v2
	v_mov_b32_e32 v76, v2
	v_mov_b32_e32 v77, v2
	v_mov_b32_e32 v82, v2
	v_mov_b32_e32 v83, v2
	v_mov_b32_e32 v84, v2
	v_mov_b32_e32 v85, v2
	v_mov_b32_e32 v98, v2
	v_mov_b32_e32 v99, v2
	v_mov_b32_e32 v100, v2
	v_mov_b32_e32 v101, v2
	v_mov_b32_e32 v102, v2
	v_mov_b32_e32 v103, v2
	v_mov_b32_e32 v104, v2
	v_mov_b32_e32 v105, v2
	v_mov_b32_e32 v106, v2
	v_mov_b32_e32 v107, v2
	v_mov_b32_e32 v108, v2
	v_mov_b32_e32 v109, v2
	v_mov_b32_e32 v110, v2
	v_mov_b32_e32 v111, v2
	v_mov_b32_e32 v112, v2
	v_mov_b32_e32 v113, v2
	v_mov_b32_e32 v78, v2
	v_mov_b32_e32 v79, v2
	v_mov_b32_e32 v80, v2
	v_mov_b32_e32 v81, v2
	v_mov_b32_e32 v86, v2
	v_mov_b32_e32 v87, v2
	v_mov_b32_e32 v88, v2
	v_mov_b32_e32 v89, v2
	v_mov_b32_e32 v90, v2
	v_mov_b32_e32 v91, v2
	v_mov_b32_e32 v92, v2
	v_mov_b32_e32 v93, v2
	v_mov_b32_e32 v94, v2
	v_mov_b32_e32 v95, v2
	v_mov_b32_e32 v96, v2
	v_mov_b32_e32 v97, v2
	v_mov_b32_e32 v114, v2
	v_mov_b32_e32 v115, v2
	v_mov_b32_e32 v116, v2
	v_mov_b32_e32 v117, v2
	v_mov_b32_e32 v118, v2
	v_mov_b32_e32 v119, v2
	v_mov_b32_e32 v120, v2
	v_mov_b32_e32 v121, v2
	v_mov_b32_e32 v122, v2
	v_mov_b32_e32 v123, v2
	v_mov_b32_e32 v124, v2
	v_mov_b32_e32 v125, v2
	v_mov_b32_e32 v126, v2
	v_mov_b32_e32 v127, v2
	v_mov_b32_e32 v128, v2
	v_mov_b32_e32 v129, v2
	.p2align 6

.LBB0_2593:
	s_ashr_i32 s11, s10, 31
	s_lshl_b64 s[12:13], s[10:11], 20
	s_add_u32 s12, s26, s12
	s_addc_u32 s13, s27, s13
	s_and_b64 s[14:15], s[2:3], exec
	s_cselect_b32 s11, s13, s21
	s_cselect_b32 s62, s12, s20
	s_ashr_i32 s9, s8, 31
	s_lshl_b64 s[14:15], s[8:9], 20
	s_add_u32 s14, s28, s14
	s_addc_u32 s15, s29, s15
	s_and_b64 s[22:23], s[2:3], exec
	s_cselect_b32 s9, s15, s19
	s_cselect_b32 s63, s14, s18
	s_add_u32 s64, s18, 0x100
	s_addc_u32 s65, s19, 0
	s_add_u32 s18, s20, 0x80080
	s_addc_u32 s19, s21, 0
	s_add_u32 s66, s20, 0x100
	v_mov_b32_e32 v2, 0
	s_addc_u32 s67, s21, 0
	s_mov_b32 s70, -2
	v_mov_b32_e32 v3, v2
	v_mov_b32_e32 v4, v2
	v_mov_b32_e32 v5, v2
	v_mov_b32_e32 v6, v2
	v_mov_b32_e32 v7, v2
	v_mov_b32_e32 v8, v2
	v_mov_b32_e32 v9, v2
	v_mov_b32_e32 v18, v2
	v_mov_b32_e32 v19, v2
	v_mov_b32_e32 v20, v2
	v_mov_b32_e32 v21, v2
	v_mov_b32_e32 v22, v2
	v_mov_b32_e32 v23, v2
	v_mov_b32_e32 v24, v2
	v_mov_b32_e32 v25, v2
	v_mov_b32_e32 v34, v2
	v_mov_b32_e32 v35, v2
	v_mov_b32_e32 v36, v2
	v_mov_b32_e32 v37, v2
	v_mov_b32_e32 v38, v2
	v_mov_b32_e32 v39, v2
	v_mov_b32_e32 v40, v2
	v_mov_b32_e32 v41, v2
	v_mov_b32_e32 v50, v2
	v_mov_b32_e32 v51, v2
	v_mov_b32_e32 v52, v2
	v_mov_b32_e32 v53, v2
	v_mov_b32_e32 v54, v2
	v_mov_b32_e32 v55, v2
	v_mov_b32_e32 v56, v2
	v_mov_b32_e32 v57, v2
	v_mov_b32_e32 v10, v2
	v_mov_b32_e32 v11, v2
	v_mov_b32_e32 v12, v2
	v_mov_b32_e32 v13, v2
	v_mov_b32_e32 v14, v2
	v_mov_b32_e32 v15, v2
	v_mov_b32_e32 v16, v2
	v_mov_b32_e32 v17, v2
	v_mov_b32_e32 v26, v2
	v_mov_b32_e32 v27, v2
	v_mov_b32_e32 v28, v2
	v_mov_b32_e32 v29, v2
	v_mov_b32_e32 v30, v2
	v_mov_b32_e32 v31, v2
	v_mov_b32_e32 v32, v2
	v_mov_b32_e32 v33, v2
	v_mov_b32_e32 v42, v2
	v_mov_b32_e32 v43, v2
	v_mov_b32_e32 v44, v2
	v_mov_b32_e32 v45, v2
	v_mov_b32_e32 v46, v2
	v_mov_b32_e32 v47, v2
	v_mov_b32_e32 v48, v2
	v_mov_b32_e32 v49, v2
	v_mov_b32_e32 v58, v2
	v_mov_b32_e32 v59, v2
	v_mov_b32_e32 v60, v2
	v_mov_b32_e32 v61, v2
	v_mov_b32_e32 v62, v2
	v_mov_b32_e32 v63, v2
	v_mov_b32_e32 v64, v2
	v_mov_b32_e32 v65, v2
	v_mov_b32_e32 v66, v2
	v_mov_b32_e32 v67, v2
	v_mov_b32_e32 v68, v2
	v_mov_b32_e32 v69, v2
	v_mov_b32_e32 v70, v2
	v_mov_b32_e32 v71, v2
	v_mov_b32_e32 v72, v2
	v_mov_b32_e32 v73, v2
	v_mov_b32_e32 v82, v2
	v_mov_b32_e32 v83, v2
	v_mov_b32_e32 v84, v2
	v_mov_b32_e32 v85, v2
	v_mov_b32_e32 v86, v2
	v_mov_b32_e32 v87, v2
	v_mov_b32_e32 v88, v2
	v_mov_b32_e32 v89, v2
	v_mov_b32_e32 v98, v2
	v_mov_b32_e32 v99, v2
	v_mov_b32_e32 v100, v2
	v_mov_b32_e32 v101, v2
	v_mov_b32_e32 v102, v2
	v_mov_b32_e32 v103, v2
	v_mov_b32_e32 v104, v2
	v_mov_b32_e32 v105, v2
	v_mov_b32_e32 v114, v2
	v_mov_b32_e32 v115, v2
	v_mov_b32_e32 v116, v2
	v_mov_b32_e32 v117, v2
	v_mov_b32_e32 v118, v2
	v_mov_b32_e32 v119, v2
	v_mov_b32_e32 v120, v2
	v_mov_b32_e32 v121, v2
	v_mov_b32_e32 v74, v2
	v_mov_b32_e32 v75, v2
	v_mov_b32_e32 v76, v2
	v_mov_b32_e32 v77, v2
	v_mov_b32_e32 v78, v2
	v_mov_b32_e32 v79, v2
	v_mov_b32_e32 v80, v2
	v_mov_b32_e32 v81, v2
	v_mov_b32_e32 v90, v2
	v_mov_b32_e32 v91, v2
	v_mov_b32_e32 v92, v2
	v_mov_b32_e32 v93, v2
	v_mov_b32_e32 v94, v2
	v_mov_b32_e32 v95, v2
	v_mov_b32_e32 v96, v2
	v_mov_b32_e32 v97, v2
	v_mov_b32_e32 v106, v2
	v_mov_b32_e32 v107, v2
	v_mov_b32_e32 v108, v2
	v_mov_b32_e32 v109, v2
	v_mov_b32_e32 v110, v2
	v_mov_b32_e32 v111, v2
	v_mov_b32_e32 v112, v2
	v_mov_b32_e32 v113, v2
	v_mov_b32_e32 v122, v2
	v_mov_b32_e32 v123, v2
	v_mov_b32_e32 v124, v2
	v_mov_b32_e32 v125, v2
	v_mov_b32_e32 v126, v2
	v_mov_b32_e32 v127, v2
	v_mov_b32_e32 v128, v2
	v_mov_b32_e32 v129, v2
	.p2align 6

.LBB0_2791:
	s_ashr_i32 s21, s20, 31
	s_lshl_b64 s[22:23], s[20:21], 15
	s_add_u32 s22, s37, s22
	s_addc_u32 s23, s40, s23
	s_and_b64 s[24:25], s[2:3], exec
	s_cselect_b32 s21, s23, s31
	s_cselect_b32 s63, s22, s30
	s_ashr_i32 s19, s18, 31
	s_lshl_b64 s[24:25], s[18:19], 15
	s_add_u32 s24, s41, s24
	s_addc_u32 s25, s42, s25
	s_and_b64 s[34:35], s[2:3], exec
	s_cselect_b32 s19, s25, s29
	s_cselect_b32 s64, s24, s28
	s_add_u32 s65, s28, 0x80000
	s_addc_u32 s66, s29, 0
	s_add_u32 s28, s30, 0x204000
	s_addc_u32 s29, s31, 0
	s_add_u32 s67, s30, 0x400000
	v_mov_b32_e32 v2, 0
	s_addc_u32 s68, s31, 0
	s_mov_b32 s69, -2
	v_mov_b32_e32 v3, v2
	v_mov_b32_e32 v4, v2
	v_mov_b32_e32 v5, v2
	v_mov_b32_e32 v6, v2
	v_mov_b32_e32 v7, v2
	s_waitcnt vmcnt(25)
	v_mov_b32_e32 v8, v2
	s_waitcnt vmcnt(24)
	v_mov_b32_e32 v9, v2
	s_waitcnt vmcnt(4)
	v_mov_b32_e32 v18, v2
	v_mov_b32_e32 v19, v2
	v_mov_b32_e32 v20, v2
	v_mov_b32_e32 v21, v2
	s_waitcnt vmcnt(2)
	v_mov_b32_e32 v22, v2
	v_mov_b32_e32 v23, v2
	v_mov_b32_e32 v24, v2
	v_mov_b32_e32 v25, v2
	v_mov_b32_e32 v34, v2
	v_mov_b32_e32 v35, v2
	v_mov_b32_e32 v36, v2
	v_mov_b32_e32 v37, v2
	v_mov_b32_e32 v38, v2
	v_mov_b32_e32 v39, v2
	v_mov_b32_e32 v40, v2
	v_mov_b32_e32 v41, v2
	v_mov_b32_e32 v50, v2
	v_mov_b32_e32 v51, v2
	v_mov_b32_e32 v52, v2
	v_mov_b32_e32 v53, v2
	v_mov_b32_e32 v54, v2
	v_mov_b32_e32 v55, v2
	v_mov_b32_e32 v56, v2
	v_mov_b32_e32 v57, v2
	v_mov_b32_e32 v10, v2
	v_mov_b32_e32 v11, v2
	v_mov_b32_e32 v12, v2
	v_mov_b32_e32 v13, v2
	v_mov_b32_e32 v14, v2
	v_mov_b32_e32 v15, v2
	v_mov_b32_e32 v16, v2
	v_mov_b32_e32 v17, v2
	v_mov_b32_e32 v26, v2
	v_mov_b32_e32 v27, v2
	v_mov_b32_e32 v28, v2
	v_mov_b32_e32 v29, v2
	v_mov_b32_e32 v30, v2
	v_mov_b32_e32 v31, v2
	s_waitcnt vmcnt(1)
	v_mov_b32_e32 v32, v2
	s_waitcnt vmcnt(0)
	v_mov_b32_e32 v33, v2
	v_mov_b32_e32 v42, v2
	v_mov_b32_e32 v43, v2
	v_mov_b32_e32 v44, v2
	v_mov_b32_e32 v45, v2
	v_mov_b32_e32 v46, v2
	v_mov_b32_e32 v47, v2
	v_mov_b32_e32 v48, v2
	v_mov_b32_e32 v49, v2
	v_mov_b32_e32 v58, v2
	v_mov_b32_e32 v59, v2
	v_mov_b32_e32 v60, v2
	v_mov_b32_e32 v61, v2
	v_mov_b32_e32 v62, v2
	v_mov_b32_e32 v63, v2
	v_mov_b32_e32 v64, v2
	v_mov_b32_e32 v65, v2
	v_mov_b32_e32 v66, v2
	v_mov_b32_e32 v67, v2
	v_mov_b32_e32 v68, v2
	v_mov_b32_e32 v69, v2
	v_mov_b32_e32 v70, v2
	v_mov_b32_e32 v71, v2
	v_mov_b32_e32 v72, v2
	v_mov_b32_e32 v73, v2
	v_mov_b32_e32 v74, v2
	v_mov_b32_e32 v75, v2
	v_mov_b32_e32 v76, v2
	v_mov_b32_e32 v77, v2
	v_mov_b32_e32 v82, v2
	v_mov_b32_e32 v83, v2
	v_mov_b32_e32 v84, v2
	v_mov_b32_e32 v85, v2
	v_mov_b32_e32 v98, v2
	v_mov_b32_e32 v99, v2
	v_mov_b32_e32 v100, v2
	v_mov_b32_e32 v101, v2
	v_mov_b32_e32 v102, v2
	v_mov_b32_e32 v103, v2
	v_mov_b32_e32 v104, v2
	v_mov_b32_e32 v105, v2
	v_mov_b32_e32 v106, v2
	v_mov_b32_e32 v107, v2
	v_mov_b32_e32 v108, v2
	v_mov_b32_e32 v109, v2
	v_mov_b32_e32 v114, v2
	v_mov_b32_e32 v115, v2
	v_mov_b32_e32 v116, v2
	v_mov_b32_e32 v117, v2
	v_mov_b32_e32 v78, v2
	v_mov_b32_e32 v79, v2
	v_mov_b32_e32 v80, v2
	v_mov_b32_e32 v81, v2
	v_mov_b32_e32 v86, v2
	v_mov_b32_e32 v87, v2
	v_mov_b32_e32 v88, v2
	v_mov_b32_e32 v89, v2
	v_mov_b32_e32 v90, v2
	v_mov_b32_e32 v91, v2
	v_mov_b32_e32 v92, v2
	v_mov_b32_e32 v93, v2
	v_mov_b32_e32 v94, v2
	v_mov_b32_e32 v95, v2
	v_mov_b32_e32 v96, v2
	v_mov_b32_e32 v97, v2
	v_mov_b32_e32 v110, v2
	v_mov_b32_e32 v111, v2
	v_mov_b32_e32 v112, v2
	v_mov_b32_e32 v113, v2
	v_mov_b32_e32 v118, v2
	v_mov_b32_e32 v119, v2
	v_mov_b32_e32 v120, v2
	v_mov_b32_e32 v121, v2
	v_mov_b32_e32 v122, v2
	v_mov_b32_e32 v123, v2
	v_mov_b32_e32 v124, v2
	v_mov_b32_e32 v125, v2
	v_mov_b32_e32 v126, v2
	v_mov_b32_e32 v127, v2
	v_mov_b32_e32 v128, v2
	v_mov_b32_e32 v129, v2
	.p2align 6
